# gnorm inside GEMM2 K-loop (LDS ring, 3 units ahead) on the flips-deleted base + side_gemm1 coalesced
# baseline (speedup 1.0000x reference)
; template <class Epi, class Sched, bool ALIGN_EPI = false, bool SP2 = false>
; __device__ __forceinline__ void gemm_phase(PG8_LAS unsigned char* lds, const Gemm g, const Sched& S, const Epi& E) {
;     ...
;         const bool has_next = S.next(ui + 1, nxt);
;         const char* nA = has_next ? (const char*)g.A + (size_t)nxt.pm * tstep : cA; const char* nB = has_next ? (const char*)g.Bt + (size_t)nxt.pn * tstep : cB;
;         for (int t = 0; t < nt; t += 2) {
;             const bool last = (t == nt - 2);
;             const char* a1 = cA + (size_t)(t + 1) * kstep;
;             const char* a2 = last ? nA : cA + (size_t)(t + 2) * kstep; const char* b2 = last ? nB : cB + (size_t)(t + 2) * kstep;
;             const char* a3 = a2 + kstep; const char* b3 = b2 + kstep;
;     ...
; #pragma unroll
;         for (int a = 0; a < 2; ++a)
; #pragma unroll
;             for (int b = 0; b < 2; ++b)
; #pragma unroll
;                 for (int m = 0; m < 4; ++m)
; #pragma unroll
;                     for (int n = 0; n < 2; ++n) acc[a][b][m][n] = (f32x4){0.f, 0.f, 0.f, 0.f};
.LBB0_85:
	s_ashr_i32 s29, s28, 31
	s_lshl_b64 s[26:27], s[28:29], 20
	s_add_u32 s30, s22, s26
	s_addc_u32 s31, s23, s27
	s_and_b64 s[26:27], s[36:37], exec
	s_cselect_b32 s29, s31, s41
	s_cselect_b32 s50, s30, s40
	s_ashr_i32 s19, s18, 31
	s_lshl_b64 s[26:27], s[18:19], 20
	v_readlane_b32 s34, v254, 40
	v_readlane_b32 s35, v254, 41
	s_add_u32 s34, s34, s26
	s_addc_u32 s35, s35, s27
	s_and_b64 s[26:27], s[36:37], exec
	s_cselect_b32 s19, s35, s39
	s_cselect_b32 s51, s34, s38
	s_add_u32 s52, s38, 0x100
	s_addc_u32 s53, s39, 0
	s_add_u32 s38, s40, 0x80080
	v_mov_b32_e32 v4, 0
	s_addc_u32 s39, s41, 0
	s_mov_b32 s54, -2
	v_mov_b32_e32 v5, v4
	v_mov_b32_e32 v6, v4
	v_mov_b32_e32 v7, v4
	v_mov_b32_e32 v8, v4
	v_mov_b32_e32 v9, v4
	v_mov_b32_e32 v10, v4
	v_mov_b32_e32 v11, v4
	v_mov_b32_e32 v16, v4
	v_mov_b32_e32 v17, v4
	v_mov_b32_e32 v18, v4
	v_mov_b32_e32 v19, v4
	v_mov_b32_e32 v24, v4
	v_mov_b32_e32 v25, v4
	v_mov_b32_e32 v26, v4
	v_mov_b32_e32 v27, v4
	s_waitcnt vmcnt(0)
	v_mov_b32_e32 v32, v4
	v_mov_b32_e32 v33, v4
	v_mov_b32_e32 v34, v4
	v_mov_b32_e32 v35, v4
	v_mov_b32_e32 v40, v4
	v_mov_b32_e32 v41, v4
	v_mov_b32_e32 v42, v4
	v_mov_b32_e32 v43, v4
	v_mov_b32_e32 v48, v4
	v_mov_b32_e32 v49, v4
	v_mov_b32_e32 v50, v4
	v_mov_b32_e32 v51, v4
	v_mov_b32_e32 v56, v4
	v_mov_b32_e32 v57, v4
	v_mov_b32_e32 v58, v4
	v_mov_b32_e32 v59, v4
	v_mov_b32_e32 v12, v4
	v_mov_b32_e32 v13, v4
	v_mov_b32_e32 v14, v4
	v_mov_b32_e32 v15, v4
	v_mov_b32_e32 v20, v4
	v_mov_b32_e32 v21, v4
	v_mov_b32_e32 v22, v4
	v_mov_b32_e32 v23, v4
	v_mov_b32_e32 v28, v4
	v_mov_b32_e32 v29, v4
	v_mov_b32_e32 v30, v4
	v_mov_b32_e32 v31, v4
	v_mov_b32_e32 v36, v4
	v_mov_b32_e32 v37, v4
	v_mov_b32_e32 v38, v4
	v_mov_b32_e32 v39, v4
	v_mov_b32_e32 v44, v4
	v_mov_b32_e32 v45, v4
	v_mov_b32_e32 v46, v4
	v_mov_b32_e32 v47, v4
	v_mov_b32_e32 v52, v4
	v_mov_b32_e32 v53, v4
	v_mov_b32_e32 v54, v4
	v_mov_b32_e32 v55, v4
	v_mov_b32_e32 v60, v4
	v_mov_b32_e32 v61, v4
	v_mov_b32_e32 v62, v4
	v_mov_b32_e32 v63, v4
	v_mov_b32_e32 v64, v4
	v_mov_b32_e32 v65, v4
	v_mov_b32_e32 v66, v4
	v_mov_b32_e32 v67, v4
	v_mov_b32_e32 v68, v4
	v_mov_b32_e32 v69, v4
	v_mov_b32_e32 v70, v4
	v_mov_b32_e32 v71, v4
	v_mov_b32_e32 v72, v4
	v_mov_b32_e32 v73, v4
	v_mov_b32_e32 v74, v4
	v_mov_b32_e32 v75, v4
	v_mov_b32_e32 v84, v4
	v_mov_b32_e32 v85, v4
	v_mov_b32_e32 v86, v4
	v_mov_b32_e32 v87, v4
	v_mov_b32_e32 v88, v4
	v_mov_b32_e32 v89, v4
	v_mov_b32_e32 v90, v4
	v_mov_b32_e32 v91, v4
	v_mov_b32_e32 v100, v4
	v_mov_b32_e32 v101, v4
	v_mov_b32_e32 v102, v4
	v_mov_b32_e32 v103, v4
	v_mov_b32_e32 v104, v4
	v_mov_b32_e32 v105, v4
	v_mov_b32_e32 v106, v4
	v_mov_b32_e32 v107, v4
	v_mov_b32_e32 v116, v4
	v_mov_b32_e32 v117, v4
	v_mov_b32_e32 v118, v4
	v_mov_b32_e32 v119, v4
	v_mov_b32_e32 v120, v4
	v_mov_b32_e32 v121, v4
	v_mov_b32_e32 v122, v4
	v_mov_b32_e32 v123, v4
	v_mov_b32_e32 v76, v4
	v_mov_b32_e32 v77, v4
	v_mov_b32_e32 v78, v4
	v_mov_b32_e32 v79, v4
	v_mov_b32_e32 v80, v4
	v_mov_b32_e32 v81, v4
	v_mov_b32_e32 v82, v4
	v_mov_b32_e32 v83, v4
	v_mov_b32_e32 v92, v4
	v_mov_b32_e32 v93, v4
	v_mov_b32_e32 v94, v4
	v_mov_b32_e32 v95, v4
	v_mov_b32_e32 v96, v4
	v_mov_b32_e32 v97, v4
	v_mov_b32_e32 v98, v4
	v_mov_b32_e32 v99, v4
	v_mov_b32_e32 v108, v4
	v_mov_b32_e32 v109, v4
	v_mov_b32_e32 v110, v4
	v_mov_b32_e32 v111, v4
	v_mov_b32_e32 v112, v4
	v_mov_b32_e32 v113, v4
	v_mov_b32_e32 v114, v4
	v_mov_b32_e32 v115, v4
	v_mov_b32_e32 v124, v4
	v_mov_b32_e32 v125, v4
	v_mov_b32_e32 v126, v4
	v_mov_b32_e32 v127, v4
	v_mov_b32_e32 v128, v4
	v_mov_b32_e32 v129, v4
	v_mov_b32_e32 v130, v4
	v_mov_b32_e32 v131, v4
	s_setprio 0

; #define GAS __attribute__((address_space(1)))
; __device__ __forceinline__ gws_t launder_s(const void* p0) { unsigned char* p = (unsigned char*)p0; asm volatile("" : "+s"(p)); return (gws_t)p; }
; __device__ __forceinline__ int launder_v(int v) { asm volatile("" : "+v"(v)); return v; }
; __device__ __forceinline__ int grid_x() { int g = (int)gridDim.x; asm volatile("" : "+s"(g)); return g; }
; __device__ __forceinline__ void unpack8(const v4u v, float (&f)[8]) { f[0] = bflo(v.x); f[1] = bfhi(v.x); f[2] = bflo(v.y); f[3] = bfhi(v.y); f[4] = bflo(v.z); f[5] = bfhi(v.z); f[6] = bflo(v.w); f[7] = bfhi(v.w); }
; __device__ __forceinline__ v4u pack8(const float (&f)[8]) { v4u o; o.x = cvt_pk_bf16(f[0], f[1]); o.y = cvt_pk_bf16(f[2], f[3]); o.z = cvt_pk_bf16(f[4], f[5]); o.w = cvt_pk_bf16(f[6], f[7]); return o; }
; __device__ __forceinline__ void phase_gnorm(const Params& P, int seg) {
;     GAS bf16* ypre = (GAS bf16*)(launder_s(P.ws) + WS_YPRE);
;     const int tidl = launder_v(threadIdx.x); const int lane = tidl & 63, gw = blockIdx.x * 8 + (tidl >> 6), NGW = grid_x() * 8;
;     const int nrows = (seg == 0) ? RS + 16 : RS;
;     for (int rr = gw; rr < nrows; rr += NGW) { const int row = (rr < RS) ? rr : rr + 48; GAS bf16* p = ypre + (size_t)row * DINNER + lane * 8;
;         v4u raw[8];
; #pragma unroll
;         for (int g = 0; g < 8; ++g) raw[g] = *(const GAS v4u*)(p + g * 512);
; #pragma unroll
;         for (int g = 0; g < 8; ++g) { float f[8]; unpack8(raw[g], f); float s = 0.f;
; #pragma unroll
;             for (int e = 0; e < 8; ++e) s += f[e] * f[e];
;             s = wave_sum(s); const float rs = rsqrtf(s * (1.f / 512.f) + EPS);
; #pragma unroll
;             for (int e = 0; e < 8; ++e) f[e] *= rs;
;             *(GAS v4u*)(p + g * 512) = pack8(f); } }
.LBB0_391:
	s_or_b64 exec, exec, s[0:1]
	s_mov_b64 s[0:1], s[80:81]
	s_waitcnt lgkmcnt(0)
	v_mov_b32_e32 v4, v172
	s_and_b64 s[14:15], s[36:37], exec
	s_barrier
	s_mov_b64 exec, -1
	v_and_b32_e32 v236, 63, v172
	v_lshlrev_b32_e32 v236, 4, v236
	v_lshrrev_b32_e32 v237, 6, v172
	v_mul_u32_u24_e32 v237, 0xc00, v237
	v_add_u32_e32 v237, v237, v236
	v_add_u32_e32 v237, 0x21100, v237
	v_readfirstlane_b32 s63, v172
	v_readlane_b32 s66, v254, 38
	v_readfirstlane_b32 s69, v237
	s_nop 3
	s_lshr_b32 s63, s63, 6
	s_lshl_b32 s64, s2, 3
	s_add_i32 s63, s63, s64
	s_mov_b32 s84, 0
	s_mov_b32 s32, 0
	s_add_u32 s67, s80, 0x304f1000
	s_addc_u32 s68, s81, 0
	s_lshl_b32 s64, s63, 13
	s_add_u32 s98, s67, s64
	s_addc_u32 s99, s68, 0
	s_mov_b64 s[100:101], s[98:99]
	s_mov_b32 m0, s69
	s_nop 0
	global_load_lds_dwordx4 v236, s[100:101]
	s_add_u32 s100, s100, 0x400
	s_addc_u32 s101, s101, 0
	s_add_i32 m0, s69, 0x400
	s_nop 0
	global_load_lds_dwordx4 v236, s[100:101]
	s_add_u32 s100, s100, 0x400
	s_addc_u32 s101, s101, 0
	s_add_i32 m0, s69, 0x800
	s_nop 0
	global_load_lds_dwordx4 v236, s[100:101]
	s_add_u32 s100, s100, 0x400
	s_addc_u32 s101, s101, 0
	s_cmp_lg_u32 s66, 0
	s_cbranch_scc1 .Lgn_noextra
	s_cmp_gt_u32 s63, 127
	s_cbranch_scc1 .Lgn_noextra
	s_lshr_b32 s64, s63, 3
	s_add_i32 s64, s64, 0x2030
	s_lshl_b32 s64, s64, 13
	s_and_b32 s65, s63, 7
	s_lshl_b32 s65, s65, 10
	s_add_i32 s64, s64, s65
	s_add_u32 s70, s67, s64
	s_addc_u32 s71, s68, 0
	global_load_dwordx4 v[244:247], v236, s[70:71]
	s_waitcnt vmcnt(0)
	v_lshlrev_b32_e32 v232, 16, v244
	v_and_b32_e32 v233, 0xffff0000, v244
	v_mul_f32_e32 v234, v232, v232
	v_fmac_f32_e32 v234, v233, v233
	v_lshlrev_b32_e32 v232, 16, v245
	v_and_b32_e32 v233, 0xffff0000, v245
	v_fmac_f32_e32 v234, v232, v232
	v_fmac_f32_e32 v234, v233, v233
	v_lshlrev_b32_e32 v232, 16, v246
	v_and_b32_e32 v233, 0xffff0000, v246
	v_fmac_f32_e32 v234, v232, v232
	v_fmac_f32_e32 v234, v233, v233
	v_lshlrev_b32_e32 v232, 16, v247
	v_and_b32_e32 v233, 0xffff0000, v247
	v_fmac_f32_e32 v234, v232, v232
	v_fmac_f32_e32 v234, v233, v233
	s_nop 1
	v_add_f32_dpp v234, v234, v234 quad_perm:[1,0,3,2] row_mask:0xf bank_mask:0xf
	s_nop 1
	v_add_f32_dpp v234, v234, v234 quad_perm:[2,3,0,1] row_mask:0xf bank_mask:0xf
	s_nop 1
	v_add_f32_dpp v234, v234, v234 row_half_mirror row_mask:0xf bank_mask:0xf
	s_nop 1
	v_add_f32_dpp v234, v234, v234 row_mirror row_mask:0xf bank_mask:0xf
	s_nop 1
	v_add_f32_dpp v234, v234, v234 row_bcast:15 row_mask:0xa bank_mask:0xf
	s_nop 1
	v_add_f32_dpp v234, v234, v234 row_bcast:31 row_mask:0xc bank_mask:0xf
	s_nop 1
	v_readlane_b32 s66, v234, 63
	s_nop 3
	v_mov_b32_e32 v235, s66
	v_fmamk_f32 v235, v235, 0x3b000000, v176
	v_rsq_f32_e32 v235, v235
	s_nop 1
	v_lshlrev_b32_e32 v232, 16, v244
	v_and_b32_e32 v233, 0xffff0000, v244
	v_mul_f32_e32 v232, v235, v232
	v_mul_f32_e32 v233, v235, v233
	v_cvt_pk_bf16_f32 v244, v232, v233
	v_lshlrev_b32_e32 v232, 16, v245
	v_and_b32_e32 v233, 0xffff0000, v245
	v_mul_f32_e32 v232, v235, v232
	v_mul_f32_e32 v233, v235, v233
	v_cvt_pk_bf16_f32 v245, v232, v233
	v_lshlrev_b32_e32 v232, 16, v246
	v_and_b32_e32 v233, 0xffff0000, v246
	v_mul_f32_e32 v232, v235, v232
	v_mul_f32_e32 v233, v235, v233
	v_cvt_pk_bf16_f32 v246, v232, v233
	v_lshlrev_b32_e32 v232, 16, v247
	v_and_b32_e32 v233, 0xffff0000, v247
	v_mul_f32_e32 v232, v235, v232
	v_mul_f32_e32 v233, v235, v233
	v_cvt_pk_bf16_f32 v247, v232, v233
	global_store_dwordx4 v236, v[244:247], s[70:71]
.Lgn_noextra:
	s_mov_b64 s[36:37], -1
; #define PG8_STAGE(bufoff, gbase, voff) do { _Pragma("unroll") for (int _i = 0; _i < 2; ++_i) \
;         __builtin_amdgcn_global_load_lds((const unsigned*)((const char*)(gbase) + (voff)[_i]), (PG8_LAS unsigned*)(lds + (bufoff) + ldsw + _i * 8192), 16, 0, 0); } while (0)
; #define PG8_WAIT_V(n) asm volatile("s_waitcnt vmcnt(" #n ")" ::: "memory")
; #define PG8_BAR __builtin_amdgcn_s_barrier()
; template <class Epi, class Sched, bool ALIGN_EPI = false, bool SP2 = false>
; __device__ __forceinline__ void gemm_phase(PG8_LAS unsigned char* lds, const Gemm g, const Sched& S, const Epi& E) {
;     ...
;     for (int i = 0; i < 2; ++i) { int R, C; stage_rc(tid * 16 + i * 8192, R, C); const int Rb = Epi::PERM ? ((R & ~31) + perm32(R & 31)) : R;
;         voffA[i] = (unsigned)(R * K + C) * 2u; voffB[i] = (unsigned)(Rb * K + C) * 2u; }
;     const size_t kstep = (size_t)(BK * 2);
;     const size_t hstep = (size_t)HALF * K * 2;
;     const size_t tstep = 2 * hstep;
;     const unsigned ldsw = (unsigned)wid * 1024u;
;     const int aoff = lds_byte(wr * 64 + fr, fq * 8), boff = lds_byte(wc * 32 + fr, fq * 8);
;     ...
;     if constexpr (SP2) {
;         PG8_STAGE(PG8_SB(0, 0), cB, voffB); PG8_STAGE(PG8_SB(0, 1), cB + hstep, voffB); PG8_STAGE(PG8_SA(0, 0), cA, voffA); PG8_STAGE(PG8_SA(0, 1), cA + hstep, voffA);
;         if (wr == 1) PG8_BAR;
;         PG8_WAIT_V(2); PG8_BAR;
;         PG8_STAGE(PG8_SB(1, 0), cB + kstep, voffB); PG8_STAGE(PG8_SA(1, 0), cA + kstep, voffA); PG8_STAGE(PG8_SB(1, 1), cB + hstep + kstep, voffB);
;         PG8_WAIT_V(6); PG8_BAR;
.LBB0_394:
	s_or_b64 exec, exec, s[36:37]
	v_readlane_b32 s0, v254, 40
	v_readlane_b32 s1, v254, 41
	s_mov_b32 s18, s82
	v_writelane_b32 v254, s0, 40
	v_mov_b32_e32 v18, v172
	s_nop 0
	v_writelane_b32 v254, s1, 41
	v_readlane_b32 s0, v253, 47
	v_readlane_b32 s1, v253, 48
	v_readfirstlane_b32 s9, v18
	s_and_b64 vcc, exec, s[0:1]
	s_cbranch_vccz .LBB0_414
	v_lshlrev_b32_e32 v4, 4, v18
	v_add_u32_e32 v5, 0x2000, v4
	v_ashrrev_i32_e32 v6, 31, v5
	v_lshrrev_b32_e32 v6, 22, v6
	v_add_u32_e32 v6, v5, v6
	v_ashrrev_i32_e32 v12, 10, v6
	v_mul_i32_i24_e32 v6, 0x400, v12
	v_sub_u32_e32 v5, v5, v6
	v_lshrrev_b32_e32 v6, 4, v5
	v_bitop3_b32 v5, v6, v5, 32 bitop3:0x6c
	v_ashrrev_i32_e32 v6, 31, v5
	v_lshrrev_b32_e32 v6, 26, v6
	v_readlane_b32 s0, v254, 40
	v_add_u32_e32 v6, v5, v6
	v_lshlrev_b32_e32 v7, 3, v12
	v_readlane_b32 s1, v254, 41
	s_add_u32 s19, s0, 0x27ee1000
	v_ashrrev_i32_e32 v13, 6, v6
	v_and_b32_e32 v7, -16, v7
	s_addc_u32 s20, s1, 0
	v_add_u32_e32 v7, v13, v7
	s_add_u32 s26, s0, 0x5040000
	v_and_b32_e32 v8, 3, v13
	s_mov_b32 s0, 0xfffe0
	v_lshrrev_b32_e32 v9, 2, v7
	v_lshlrev_b32_e32 v10, 1, v7
	v_and_b32_e32 v6, 0xc0, v6
	v_and_or_b32 v8, v7, s0, v8
	v_and_b32_e32 v9, 4, v9
	v_and_b32_e32 v10, 24, v10
	v_sub_u32_e32 v5, v5, v6
	v_or3_b32 v8, v8, v9, v10
	v_lshlrev_b32_e32 v9, 5, v12
	v_ashrrev_i16_sdwa v5, v238, sext(v5) dst_sel:DWORD dst_unused:UNUSED_PAD src0_sel:DWORD src1_sel:BYTE_0
	v_and_b32_e32 v9, 32, v9
	v_bfe_i32 v14, v5, 0, 16
	v_add_lshl_u32 v5, v9, v14, 1
	v_lshl_add_u32 v144, v8, 12, v5
	v_lshl_add_u32 v146, v7, 12, v5
	v_bfe_i32 v5, v18, 27, 1
	v_lshrrev_b32_e32 v5, 22, v5
	v_add_u32_e32 v5, v4, v5
	v_and_b32_e32 v5, 0xfffffc00, v5
	v_sub_u32_e32 v4, v4, v5
	v_lshrrev_b32_e32 v5, 4, v4
	v_ashrrev_i32_e32 v6, 31, v18
	v_bitop3_b32 v4, v5, v4, 32 bitop3:0x6c
	v_lshrrev_b32_e32 v6, 26, v6
	v_ashrrev_i32_e32 v5, 31, v4
	v_add_u32_e32 v6, v18, v6
	v_lshrrev_b32_e32 v5, 26, v5
	v_ashrrev_i32_e32 v16, 6, v6
	v_add_u32_e32 v5, v4, v5
	v_lshlrev_b32_e32 v6, 3, v16
	v_ashrrev_i32_e32 v15, 6, v5
	v_and_b32_e32 v6, -16, v6
	v_add_u32_e32 v6, v15, v6
	v_and_b32_e32 v7, 3, v15
	v_lshrrev_b32_e32 v8, 2, v6
	v_lshlrev_b32_e32 v9, 1, v6
	v_and_b32_e32 v5, 0xc0, v5
	s_addc_u32 s27, s1, 0
	s_ashr_i32 s16, s9, 6
	v_and_or_b32 v7, v6, s0, v7
	v_and_b32_e32 v8, 4, v8
	v_and_b32_e32 v9, 24, v9
	v_sub_u32_e32 v4, v4, v5
	s_ashr_i32 s17, s9, 8
	s_lshl_b32 s28, s16, 10
	v_or3_b32 v7, v7, v8, v9
	v_lshlrev_b32_e32 v8, 5, v16
	v_ashrrev_i16_sdwa v4, v238, sext(v4) dst_sel:DWORD dst_unused:UNUSED_PAD src0_sel:DWORD src1_sel:BYTE_0
	v_readlane_b32 s0, v254, 2
	v_and_b32_e32 v8, 32, v8
	v_bfe_i32 v17, v4, 0, 16
	v_readlane_b32 s1, v254, 3
	s_add_u32 s0, s26, s0
	v_add_lshl_u32 v4, v8, v17, 1
	s_addc_u32 s1, s27, s1
	s_add_i32 s29, s28, 0
	v_lshl_add_u32 v174, v7, 12, v4
	s_add_i32 m0, s29, 0x10000
	v_lshl_add_u32 v148, v6, 12, v4
	global_load_lds_dwordx4 v174, s[0:1]
	s_add_i32 m0, s29, 0x12000
	s_add_u32 s14, s0, 0x80000
	global_load_lds_dwordx4 v144, s[0:1]
	s_addc_u32 s15, s1, 0
	s_add_i32 m0, s29, 0x14000
	v_mov_b32_e32 v145, v175
	global_load_lds_dwordx4 v174, s[14:15]
	s_add_i32 m0, s29, 0x16000
	v_mov_b32_e32 v149, v175
	global_load_lds_dwordx4 v144, s[14:15]
	v_readlane_b32 s14, v254, 32
	v_readlane_b32 s15, v254, 33
	s_add_u32 s14, s19, s14
	s_addc_u32 s15, s20, s15
	s_add_i32 s30, s29, 0x2000
	s_mov_b32 m0, s29
	s_add_u32 s22, s14, 0x80000
	global_load_lds_dwordx4 v148, s[14:15]
	s_mov_b32 m0, s30
	s_addc_u32 s23, s15, 0
	s_add_i32 s31, s29, 0x4000
	global_load_lds_dwordx4 v146, s[14:15]
	s_mov_b32 m0, s31
	s_add_i32 s34, s29, 0x6000
	global_load_lds_dwordx4 v148, s[22:23]
	s_mov_b32 m0, s34
	v_mov_b32_e32 v147, v175
	global_load_lds_dwordx4 v146, s[22:23]
	s_cmp_eq_u32 s17, 1
	v_lshl_add_u64 v[10:11], s[0:1], 0, v[174:175]
	v_lshl_add_u64 v[8:9], s[0:1], 0, v[144:145]
	v_lshl_add_u64 v[4:5], s[14:15], 0, v[148:149]
	s_cselect_b64 s[36:37], -1, 0
	s_cmp_lg_u32 s17, 1
	v_lshl_add_u64 v[6:7], s[14:15], 0, v[146:147]
	s_cbranch_scc1 .LBB0_397
	s_barrier

; #define PG8_STAGE(bufoff, gbase, voff) do { _Pragma("unroll") for (int _i = 0; _i < 2; ++_i) \
;         __builtin_amdgcn_global_load_lds((const unsigned*)((const char*)(gbase) + (voff)[_i]), (PG8_LAS unsigned*)(lds + (bufoff) + ldsw + _i * 8192), 16, 0, 0); } while (0)
; #define PG8_LDA(dst, b, h) do { _Pragma("unroll") for (int m = 0; m < 4; ++m) _Pragma("unroll") for (int k = 0; k < 2; ++k) dst[m][k] = *(const PG8_LAS bf16x8*)(lds + PG8_SA(b, h) + aoff + m * 2048 + k * 1024); } while (0)
; #define PG8_LDB(dst, b, h) do { _Pragma("unroll") for (int n = 0; n < 2; ++n) _Pragma("unroll") for (int k = 0; k < 2; ++k) dst[n][k] = *(const PG8_LAS bf16x8*)(lds + PG8_SB(b, h) + boff + n * 2048 + k * 1024); } while (0)
; #define PG8_MMA(ai, bj, At, Bt) do { __builtin_amdgcn_s_setprio(1); _Pragma("unroll") for (int m = 0; m < 4; ++m) _Pragma("unroll") for (int n = 0; n < 2; ++n) _Pragma("unroll") for (int k = 0; k < 2; ++k) \
;         acc[ai][bj][m][n] = __builtin_amdgcn_mfma_f32_16x16x32_bf16(Bt[n][k], At[m][k], acc[ai][bj][m][n], 0, 0, 0); __builtin_amdgcn_s_setprio(0); } while (0)
; #define PG8_WAIT_V(n) asm volatile("s_waitcnt vmcnt(" #n ")" ::: "memory")
; #define PG8_WAIT_L(n) asm volatile("s_waitcnt lgkmcnt(" #n ")" ::: "memory")
; #define PG8_BAR __builtin_amdgcn_s_barrier()
; #define PG8_SCHED __builtin_amdgcn_sched_barrier(0)
; __device__ __forceinline__ void unpack8(const v4u v, float (&f)[8]) { f[0] = bflo(v.x); f[1] = bfhi(v.x); f[2] = bflo(v.y); f[3] = bfhi(v.y); f[4] = bflo(v.z); f[5] = bfhi(v.z); f[6] = bflo(v.w); f[7] = bfhi(v.w); }
; template <class Epi, class Sched, bool ALIGN_EPI = false, bool SP2 = false>
; __device__ __forceinline__ void gemm_phase(PG8_LAS unsigned char* lds, const Gemm g, const Sched& S, const Epi& E) {
;     ...
;             PG8_LDB(B0, 0, 0); PG8_LDB(B1, 0, 1); PG8_SCHED; PG8_LDA(At, 0, 0); PG8_STAGE(PG8_SA(1, 1), a1 + hstep, voffA);
;             PG8_WAIT_V(8); PG8_WAIT_L(0); PG8_BAR; PG8_MMA(0, 0, At, B0); PG8_MMA(0, 1, At, B1); PG8_BAR; PG8_SCHED;
; __device__ __forceinline__ void phase_gnorm(const Params& P, int seg) {
;     ...
;         for (int g = 0; g < 8; ++g) { float f[8]; unpack8(raw[g], f); float s = 0.f;
; #pragma unroll
;             for (int e = 0; e < 8; ++e) s += f[e] * f[e];
;             s = wave_sum(s); const float rs = rsqrtf(s * (1.f / 512.f) + EPS);
.LBB0_407:
	s_add_u32 s14, s0, 0xfff80080
	s_addc_u32 s15, s1, -1
	s_add_i32 s59, 0, 0x10000
	s_cmp_eq_u32 s58, 28
	s_cselect_b32 s17, s23, s15
	s_cselect_b32 s16, s24, s14
	s_cselect_b32 s15, s25, s57
	s_cselect_b32 s14, s49, s51
	s_add_i32 s62, 0, 0x14000
	v_add_u32_e32 v154, s59, v171
	v_add_u32_e32 v185, s62, v171
	v_add_u32_e32 v233, s32, v237
	ds_read_b128 v[244:247], v233
	ds_read_b128 v[100:103], v154
	ds_read_b128 v[104:107], v154 offset:1024
	ds_read_b128 v[140:143], v154 offset:2048
	ds_read_b128 v[154:157], v154 offset:3072
	ds_read_b128 v[158:161], v185
	ds_read_b128 v[162:165], v185 offset:1024
	ds_read_b128 v[166:169], v185 offset:2048
	ds_read_b128 v[186:189], v185 offset:3072
	v_lshl_add_u64 v[222:223], s[0:1], 0, v[152:153]
	s_add_i32 m0, s29, 0xc000
	ds_read_b128 v[190:193], v184
	ds_read_b128 v[194:197], v184 offset:1024
	ds_read_b128 v[198:201], v184 offset:2048
	ds_read_b128 v[202:205], v184 offset:3072
	ds_read_b128 v[206:209], v184 offset:4096
	ds_read_b128 v[210:213], v184 offset:5120
	ds_read_b128 v[214:217], v184 offset:6144
	ds_read_b128 v[218:221], v184 offset:7168
	global_load_lds_dwordx4 v[222:223], off
	v_lshl_add_u64 v[222:223], s[0:1], 0, v[150:151]
	s_add_i32 m0, s29, 0xe000
	s_nop 0
	global_load_lds_dwordx4 v[222:223], off
	s_waitcnt vmcnt(10)
	s_waitcnt lgkmcnt(0)
	v_lshlrev_b32_e32 v232, 16, v244
	v_and_b32_e32 v233, 0xffff0000, v244
	v_mul_f32_e32 v234, v232, v232
	v_fmac_f32_e32 v234, v233, v233
	v_lshlrev_b32_e32 v232, 16, v245
	v_and_b32_e32 v233, 0xffff0000, v245
	v_fmac_f32_e32 v234, v232, v232
	v_fmac_f32_e32 v234, v233, v233
	v_lshlrev_b32_e32 v232, 16, v246
	v_and_b32_e32 v233, 0xffff0000, v246
	v_fmac_f32_e32 v234, v232, v232
	v_fmac_f32_e32 v234, v233, v233
	v_lshlrev_b32_e32 v232, 16, v247
	v_and_b32_e32 v233, 0xffff0000, v247
	v_fmac_f32_e32 v234, v232, v232
	v_fmac_f32_e32 v234, v233, v233
	s_nop 1
	v_add_f32_dpp v234, v234, v234 quad_perm:[1,0,3,2] row_mask:0xf bank_mask:0xf
	s_nop 1
	v_add_f32_dpp v234, v234, v234 quad_perm:[2,3,0,1] row_mask:0xf bank_mask:0xf
	s_nop 1
	v_add_f32_dpp v234, v234, v234 row_half_mirror row_mask:0xf bank_mask:0xf
	s_nop 1
	v_add_f32_dpp v234, v234, v234 row_mirror row_mask:0xf bank_mask:0xf
	s_nop 1
	v_add_f32_dpp v234, v234, v234 row_bcast:15 row_mask:0xa bank_mask:0xf
	s_nop 1
	v_add_f32_dpp v234, v234, v234 row_bcast:31 row_mask:0xc bank_mask:0xf
	s_nop 1
	v_readlane_b32 s66, v234, 63
	s_nop 3
	v_mov_b32_e32 v235, s66
	v_fmamk_f32 v235, v235, 0x3b000000, v176
	v_rsq_f32_e32 v235, v235
	s_barrier
	s_waitcnt lgkmcnt(0)
	v_mfma_f32_16x16x32_bf16 v[136:139], v[100:103], v[190:193], v[136:139]
	v_mfma_f32_16x16x32_bf16 v[132:135], v[140:143], v[190:193], v[132:135]
	v_mfma_f32_16x16x32_bf16 v[128:131], v[100:103], v[198:201], v[128:131]
	v_mfma_f32_16x16x32_bf16 v[124:127], v[140:143], v[198:201], v[124:127]
	v_mfma_f32_16x16x32_bf16 v[120:123], v[100:103], v[206:209], v[120:123]
	v_mfma_f32_16x16x32_bf16 v[116:119], v[140:143], v[206:209], v[116:119]
	v_mfma_f32_16x16x32_bf16 v[112:115], v[100:103], v[214:217], v[112:115]
	v_mfma_f32_16x16x32_bf16 v[108:111], v[140:143], v[214:217], v[108:111]
	v_mfma_f32_16x16x32_bf16 v[136:139], v[104:107], v[194:197], v[136:139]
	v_mfma_f32_16x16x32_bf16 v[132:135], v[154:157], v[194:197], v[132:135]
	v_mfma_f32_16x16x32_bf16 v[128:131], v[104:107], v[202:205], v[128:131]
	v_mfma_f32_16x16x32_bf16 v[124:127], v[154:157], v[202:205], v[124:127]
	v_mfma_f32_16x16x32_bf16 v[120:123], v[104:107], v[210:213], v[120:123]
	v_mfma_f32_16x16x32_bf16 v[116:119], v[154:157], v[210:213], v[116:119]
	v_mfma_f32_16x16x32_bf16 v[112:115], v[104:107], v[218:221], v[112:115]
	v_mfma_f32_16x16x32_bf16 v[108:111], v[154:157], v[218:221], v[108:111]
	v_mfma_f32_16x16x32_bf16 v[64:67], v[158:161], v[190:193], v[64:67]
	v_mfma_f32_16x16x32_bf16 v[60:63], v[166:169], v[190:193], v[60:63]
	v_mfma_f32_16x16x32_bf16 v[56:59], v[158:161], v[198:201], v[56:59]
	v_mfma_f32_16x16x32_bf16 v[52:55], v[166:169], v[198:201], v[52:55]
	v_mfma_f32_16x16x32_bf16 v[48:51], v[158:161], v[206:209], v[48:51]
	v_mfma_f32_16x16x32_bf16 v[44:47], v[166:169], v[206:209], v[44:47]
	v_mfma_f32_16x16x32_bf16 v[40:43], v[158:161], v[214:217], v[40:43]
	v_mfma_f32_16x16x32_bf16 v[36:39], v[166:169], v[214:217], v[36:39]
	v_mfma_f32_16x16x32_bf16 v[64:67], v[162:165], v[194:197], v[64:67]
	v_mfma_f32_16x16x32_bf16 v[60:63], v[186:189], v[194:197], v[60:63]
	v_mfma_f32_16x16x32_bf16 v[56:59], v[162:165], v[202:205], v[56:59]
	v_mfma_f32_16x16x32_bf16 v[52:55], v[186:189], v[202:205], v[52:55]
	v_mfma_f32_16x16x32_bf16 v[48:51], v[162:165], v[210:213], v[48:51]
	v_mfma_f32_16x16x32_bf16 v[44:47], v[186:189], v[210:213], v[44:47]
	v_mfma_f32_16x16x32_bf16 v[40:43], v[162:165], v[218:221], v[40:43]
	v_mfma_f32_16x16x32_bf16 v[36:39], v[186:189], v[218:221], v[36:39]
	s_barrier
; #define PG8_STAGE(bufoff, gbase, voff) do { _Pragma("unroll") for (int _i = 0; _i < 2; ++_i) \
;         __builtin_amdgcn_global_load_lds((const unsigned*)((const char*)(gbase) + (voff)[_i]), (PG8_LAS unsigned*)(lds + (bufoff) + ldsw + _i * 8192), 16, 0, 0); } while (0)
; #define PG8_LDA(dst, b, h) do { _Pragma("unroll") for (int m = 0; m < 4; ++m) _Pragma("unroll") for (int k = 0; k < 2; ++k) dst[m][k] = *(const PG8_LAS bf16x8*)(lds + PG8_SA(b, h) + aoff + m * 2048 + k * 1024); } while (0)
; #define PG8_MMA(ai, bj, At, Bt) do { __builtin_amdgcn_s_setprio(1); _Pragma("unroll") for (int m = 0; m < 4; ++m) _Pragma("unroll") for (int n = 0; n < 2; ++n) _Pragma("unroll") for (int k = 0; k < 2; ++k) \
;         acc[ai][bj][m][n] = __builtin_amdgcn_mfma_f32_16x16x32_bf16(Bt[n][k], At[m][k], acc[ai][bj][m][n], 0, 0, 0); __builtin_amdgcn_s_setprio(0); } while (0)
; #define PG8_WAIT_V(n) asm volatile("s_waitcnt vmcnt(" #n ")" ::: "memory")
; #define PG8_WAIT_L(n) asm volatile("s_waitcnt lgkmcnt(" #n ")" ::: "memory")
; #define PG8_BAR __builtin_amdgcn_s_barrier()
; #define PG8_SCHED __builtin_amdgcn_sched_barrier(0)
; #define GAS __attribute__((address_space(1)))
; __device__ __forceinline__ v4u pack8(const float (&f)[8]) { v4u o; o.x = cvt_pk_bf16(f[0], f[1]); o.y = cvt_pk_bf16(f[2], f[3]); o.z = cvt_pk_bf16(f[4], f[5]); o.w = cvt_pk_bf16(f[6], f[7]); return o; }
; template <class Epi, class Sched, bool ALIGN_EPI = false, bool SP2 = false>
; __device__ __forceinline__ void gemm_phase(PG8_LAS unsigned char* lds, const Gemm g, const Sched& S, const Epi& E) {
;     ...
;             PG8_LDA(At, 0, 1); PG8_STAGE(PG8_SB(0, 0), b2, voffB); PG8_STAGE(PG8_SB(0, 1), b2 + hstep, voffB); PG8_STAGE(PG8_SA(0, 0), a2, voffA);
;             PG8_WAIT_V(8); PG8_WAIT_L(0); PG8_BAR; PG8_MMA(1, 0, At, B0); PG8_MMA(1, 1, At, B1); PG8_BAR; PG8_SCHED;
; __device__ __forceinline__ void phase_gnorm(const Params& P, int seg) {
;     ...
; #pragma unroll
;             for (int e = 0; e < 8; ++e) f[e] *= rs;
;             *(GAS v4u*)(p + g * 512) = pack8(f); } }
	s_add_i32 s59, s59, s28
	v_lshl_add_u64 v[222:223], s[14:15], 0, v[174:175]
	s_mov_b32 m0, s59
	ds_read_b128 v[190:193], v184 offset:16384
	ds_read_b128 v[194:197], v184 offset:17408
	ds_read_b128 v[198:201], v184 offset:18432
	ds_read_b128 v[202:205], v184 offset:19456
	ds_read_b128 v[206:209], v184 offset:20480
	ds_read_b128 v[210:213], v184 offset:21504
	ds_read_b128 v[214:217], v184 offset:22528
	ds_read_b128 v[218:221], v184 offset:23552
	v_lshlrev_b32_e32 v232, 16, v244
	v_and_b32_e32 v233, 0xffff0000, v244
	v_mul_f32_e32 v232, v235, v232
	v_mul_f32_e32 v233, v235, v233
	v_cvt_pk_bf16_f32 v244, v232, v233
	v_lshlrev_b32_e32 v232, 16, v245
	v_and_b32_e32 v233, 0xffff0000, v245
	v_mul_f32_e32 v232, v235, v232
	v_mul_f32_e32 v233, v235, v233
	v_cvt_pk_bf16_f32 v245, v232, v233
	v_lshlrev_b32_e32 v232, 16, v246
	v_and_b32_e32 v233, 0xffff0000, v246
	v_mul_f32_e32 v232, v235, v232
	v_mul_f32_e32 v233, v235, v233
	v_cvt_pk_bf16_f32 v246, v232, v233
	v_lshlrev_b32_e32 v232, 16, v247
	v_and_b32_e32 v233, 0xffff0000, v247
	v_mul_f32_e32 v232, v235, v232
	v_mul_f32_e32 v233, v235, v233
	v_cvt_pk_bf16_f32 v247, v232, v233
	global_load_lds_dwordx4 v[222:223], off
	s_add_i32 m0, s59, 0x2000
	s_add_u32 s60, s14, 0x80000
	v_lshl_add_u64 v[224:225], s[14:15], 0, v[144:145]
	s_addc_u32 s61, s15, 0
	s_add_i32 s59, s62, s28
	global_load_lds_dwordx4 v[224:225], off
	v_lshl_add_u64 v[226:227], s[60:61], 0, v[174:175]
	s_mov_b32 m0, s59
	v_lshl_add_u64 v[228:229], s[16:17], 0, v[146:147]
	global_load_lds_dwordx4 v[226:227], off
	v_lshl_add_u64 v[226:227], s[60:61], 0, v[144:145]
	s_add_i32 m0, s59, 0x2000
	s_nop 0
	global_load_lds_dwordx4 v[226:227], off
	v_lshl_add_u64 v[226:227], s[16:17], 0, v[148:149]
	s_mov_b32 m0, s29
	s_nop 0
	global_load_lds_dwordx4 v[226:227], off
	s_mov_b32 m0, s30
	s_nop 0
	global_load_lds_dwordx4 v[228:229], off
	global_store_dwordx4 v236, v[244:247], s[98:99]
	s_and_b32 s63, s84, 7
	s_lshl_b32 s65, s82, 16
	s_sub_u32 s65, s65, 0x1c00
	s_cmp_eq_u32 s63, 7
	s_cselect_b32 s64, s65, 0x400
	s_add_u32 s98, s98, s64
	s_addc_u32 s99, s99, 0
	s_add_i32 s84, s84, 1
	s_add_i32 s32, s32, 0x400
	s_cmp_ge_u32 s32, 0xc00
	s_cselect_b32 s32, 0, s32
	v_readfirstlane_b32 s63, v237
	s_add_i32 s64, s32, 0x800
	s_cmp_ge_u32 s64, 0xc00
	s_cselect_b32 s65, 0xc00, 0
	s_sub_i32 s64, s64, s65
	s_add_i32 m0, s63, s64
	s_nop 0
	global_load_lds_dwordx4 v236, s[100:101]
	s_add_i32 s66, s84, 2
	s_and_b32 s66, s66, 7
	s_lshl_b32 s65, s82, 16
	s_sub_u32 s65, s65, 0x1c00
	s_cmp_eq_u32 s66, 7
	s_cselect_b32 s64, s65, 0x400
	s_add_u32 s100, s100, s64
	s_addc_u32 s101, s101, 0
	s_waitcnt vmcnt(10)
	s_waitcnt lgkmcnt(0)
	s_barrier
	s_waitcnt lgkmcnt(0)
	v_mfma_f32_16x16x32_bf16 v[96:99], v[100:103], v[190:193], v[96:99]
	v_mfma_f32_16x16x32_bf16 v[92:95], v[140:143], v[190:193], v[92:95]
	v_mfma_f32_16x16x32_bf16 v[88:91], v[100:103], v[198:201], v[88:91]
	v_mfma_f32_16x16x32_bf16 v[84:87], v[140:143], v[198:201], v[84:87]
	v_mfma_f32_16x16x32_bf16 v[80:83], v[100:103], v[206:209], v[80:83]
	v_mfma_f32_16x16x32_bf16 v[76:79], v[140:143], v[206:209], v[76:79]
	v_mfma_f32_16x16x32_bf16 v[72:75], v[100:103], v[214:217], v[72:75]
	v_mfma_f32_16x16x32_bf16 v[68:71], v[140:143], v[214:217], v[68:71]
	v_mfma_f32_16x16x32_bf16 v[96:99], v[104:107], v[194:197], v[96:99]
	v_mfma_f32_16x16x32_bf16 v[92:95], v[154:157], v[194:197], v[92:95]
	v_mfma_f32_16x16x32_bf16 v[88:91], v[104:107], v[202:205], v[88:91]
	v_mfma_f32_16x16x32_bf16 v[84:87], v[154:157], v[202:205], v[84:87]
	v_mfma_f32_16x16x32_bf16 v[80:83], v[104:107], v[210:213], v[80:83]
	v_mfma_f32_16x16x32_bf16 v[76:79], v[154:157], v[210:213], v[76:79]
	v_mfma_f32_16x16x32_bf16 v[72:75], v[104:107], v[218:221], v[72:75]
	v_mfma_f32_16x16x32_bf16 v[68:71], v[154:157], v[218:221], v[68:71]
	v_mfma_f32_16x16x32_bf16 v[32:35], v[158:161], v[190:193], v[32:35]
	v_mfma_f32_16x16x32_bf16 v[28:31], v[166:169], v[190:193], v[28:31]
	v_mfma_f32_16x16x32_bf16 v[24:27], v[158:161], v[198:201], v[24:27]
	v_mfma_f32_16x16x32_bf16 v[20:23], v[166:169], v[198:201], v[20:23]
	v_mfma_f32_16x16x32_bf16 v[16:19], v[158:161], v[206:209], v[16:19]
	v_mfma_f32_16x16x32_bf16 v[12:15], v[166:169], v[206:209], v[12:15]
	v_mfma_f32_16x16x32_bf16 v[8:11], v[158:161], v[214:217], v[8:11]
	v_mfma_f32_16x16x32_bf16 v[4:7], v[166:169], v[214:217], v[4:7]
	v_mfma_f32_16x16x32_bf16 v[32:35], v[162:165], v[194:197], v[32:35]
	v_mfma_f32_16x16x32_bf16 v[28:31], v[186:189], v[194:197], v[28:31]
	v_mfma_f32_16x16x32_bf16 v[24:27], v[162:165], v[202:205], v[24:27]
	v_mfma_f32_16x16x32_bf16 v[20:23], v[186:189], v[202:205], v[20:23]
	v_mfma_f32_16x16x32_bf16 v[16:19], v[162:165], v[210:213], v[16:19]
	v_mfma_f32_16x16x32_bf16 v[12:15], v[186:189], v[210:213], v[12:15]
	v_mfma_f32_16x16x32_bf16 v[8:11], v[162:165], v[218:221], v[8:11]
	v_mfma_f32_16x16x32_bf16 v[4:7], v[186:189], v[218:221], v[4:7]
	s_barrier
; #define PG8_STAGE(bufoff, gbase, voff) do { _Pragma("unroll") for (int _i = 0; _i < 2; ++_i) \
;         __builtin_amdgcn_global_load_lds((const unsigned*)((const char*)(gbase) + (voff)[_i]), (PG8_LAS unsigned*)(lds + (bufoff) + ldsw + _i * 8192), 16, 0, 0); } while (0)
; #define PG8_LDA(dst, b, h) do { _Pragma("unroll") for (int m = 0; m < 4; ++m) _Pragma("unroll") for (int k = 0; k < 2; ++k) dst[m][k] = *(const PG8_LAS bf16x8*)(lds + PG8_SA(b, h) + aoff + m * 2048 + k * 1024); } while (0)
; #define PG8_LDB(dst, b, h) do { _Pragma("unroll") for (int n = 0; n < 2; ++n) _Pragma("unroll") for (int k = 0; k < 2; ++k) dst[n][k] = *(const PG8_LAS bf16x8*)(lds + PG8_SB(b, h) + boff + n * 2048 + k * 1024); } while (0)
; #define PG8_MMA(ai, bj, At, Bt) do { __builtin_amdgcn_s_setprio(1); _Pragma("unroll") for (int m = 0; m < 4; ++m) _Pragma("unroll") for (int n = 0; n < 2; ++n) _Pragma("unroll") for (int k = 0; k < 2; ++k) \
;         acc[ai][bj][m][n] = __builtin_amdgcn_mfma_f32_16x16x32_bf16(Bt[n][k], At[m][k], acc[ai][bj][m][n], 0, 0, 0); __builtin_amdgcn_s_setprio(0); } while (0)
; #define PG8_WAIT_V(n) asm volatile("s_waitcnt vmcnt(" #n ")" ::: "memory")
; #define PG8_WAIT_L(n) asm volatile("s_waitcnt lgkmcnt(" #n ")" ::: "memory")
; #define PG8_BAR __builtin_amdgcn_s_barrier()
; #define PG8_SCHED __builtin_amdgcn_sched_barrier(0)
; __device__ __forceinline__ void unpack8(const v4u v, float (&f)[8]) { f[0] = bflo(v.x); f[1] = bfhi(v.x); f[2] = bflo(v.y); f[3] = bfhi(v.y); f[4] = bflo(v.z); f[5] = bfhi(v.z); f[6] = bflo(v.w); f[7] = bfhi(v.w); }
; template <class Epi, class Sched, bool ALIGN_EPI = false, bool SP2 = false>
; __device__ __forceinline__ void gemm_phase(PG8_LAS unsigned char* lds, const Gemm g, const Sched& S, const Epi& E) {
;     ...
;             PG8_LDB(B0, 1, 0); PG8_LDB(B1, 1, 1); PG8_SCHED; PG8_LDA(At, 1, 0); PG8_STAGE(PG8_SA(0, 1), a2 + hstep, voffA);
;             PG8_WAIT_V(8); PG8_WAIT_L(0); PG8_BAR; PG8_MMA(0, 0, At, B0); PG8_MMA(0, 1, At, B1); PG8_BAR; PG8_SCHED;
; __device__ __forceinline__ void phase_gnorm(const Params& P, int seg) {
;     ...
;         for (int g = 0; g < 8; ++g) { float f[8]; unpack8(raw[g], f); float s = 0.f;
; #pragma unroll
;             for (int e = 0; e < 8; ++e) s += f[e] * f[e];
;             s = wave_sum(s); const float rs = rsqrtf(s * (1.f / 512.f) + EPS);
	s_add_i32 s59, 0, 0x18000
	s_add_i32 s60, 0, 0x1c000
	v_add_u32_e32 v154, s59, v171
	v_add_u32_e32 v185, s60, v171
	v_add_u32_e32 v233, s32, v237
	ds_read_b128 v[244:247], v233
	ds_read_b128 v[100:103], v154
	ds_read_b128 v[104:107], v154 offset:1024
	ds_read_b128 v[140:143], v154 offset:2048
	ds_read_b128 v[154:157], v154 offset:3072
	ds_read_b128 v[158:161], v185
	ds_read_b128 v[162:165], v185 offset:1024
	ds_read_b128 v[166:169], v185 offset:2048
	ds_read_b128 v[186:189], v185 offset:3072
	s_add_u32 s16, s16, 0x80000
	s_addc_u32 s17, s17, 0
	s_mov_b32 m0, s31
	v_lshl_add_u64 v[230:231], s[16:17], 0, v[148:149]
	ds_read_b128 v[190:193], v184 offset:32768
	ds_read_b128 v[194:197], v184 offset:33792
	ds_read_b128 v[198:201], v184 offset:34816
	ds_read_b128 v[202:205], v184 offset:35840
	ds_read_b128 v[206:209], v184 offset:36864
	ds_read_b128 v[210:213], v184 offset:37888
	ds_read_b128 v[214:217], v184 offset:38912
	ds_read_b128 v[218:221], v184 offset:39936
	global_load_lds_dwordx4 v[230:231], off
	v_lshl_add_u64 v[230:231], s[16:17], 0, v[146:147]
	s_mov_b32 m0, s34
	s_nop 0
	global_load_lds_dwordx4 v[230:231], off
	s_waitcnt vmcnt(10)
	s_waitcnt lgkmcnt(0)
	v_lshlrev_b32_e32 v232, 16, v244
	v_and_b32_e32 v233, 0xffff0000, v244
	v_mul_f32_e32 v234, v232, v232
	v_fmac_f32_e32 v234, v233, v233
	v_lshlrev_b32_e32 v232, 16, v245
	v_and_b32_e32 v233, 0xffff0000, v245
	v_fmac_f32_e32 v234, v232, v232
	v_fmac_f32_e32 v234, v233, v233
	v_lshlrev_b32_e32 v232, 16, v246
	v_and_b32_e32 v233, 0xffff0000, v246
	v_fmac_f32_e32 v234, v232, v232
	v_fmac_f32_e32 v234, v233, v233
	v_lshlrev_b32_e32 v232, 16, v247
	v_and_b32_e32 v233, 0xffff0000, v247
	v_fmac_f32_e32 v234, v232, v232
	v_fmac_f32_e32 v234, v233, v233
	s_nop 1
	v_add_f32_dpp v234, v234, v234 quad_perm:[1,0,3,2] row_mask:0xf bank_mask:0xf
	s_nop 1
	v_add_f32_dpp v234, v234, v234 quad_perm:[2,3,0,1] row_mask:0xf bank_mask:0xf
	s_nop 1
	v_add_f32_dpp v234, v234, v234 row_half_mirror row_mask:0xf bank_mask:0xf
	s_nop 1
	v_add_f32_dpp v234, v234, v234 row_mirror row_mask:0xf bank_mask:0xf
	s_nop 1
	v_add_f32_dpp v234, v234, v234 row_bcast:15 row_mask:0xa bank_mask:0xf
	s_nop 1
	v_add_f32_dpp v234, v234, v234 row_bcast:31 row_mask:0xc bank_mask:0xf
	s_nop 1
	v_readlane_b32 s66, v234, 63
	s_nop 3
	v_mov_b32_e32 v235, s66
	v_fmamk_f32 v235, v235, 0x3b000000, v176
	v_rsq_f32_e32 v235, v235
	s_barrier
	s_waitcnt lgkmcnt(0)
	v_mfma_f32_16x16x32_bf16 v[136:139], v[100:103], v[190:193], v[136:139]
	v_mfma_f32_16x16x32_bf16 v[132:135], v[140:143], v[190:193], v[132:135]
	v_mfma_f32_16x16x32_bf16 v[128:131], v[100:103], v[198:201], v[128:131]
	v_mfma_f32_16x16x32_bf16 v[124:127], v[140:143], v[198:201], v[124:127]
	v_mfma_f32_16x16x32_bf16 v[120:123], v[100:103], v[206:209], v[120:123]
	v_mfma_f32_16x16x32_bf16 v[116:119], v[140:143], v[206:209], v[116:119]
	v_mfma_f32_16x16x32_bf16 v[112:115], v[100:103], v[214:217], v[112:115]
	v_mfma_f32_16x16x32_bf16 v[108:111], v[140:143], v[214:217], v[108:111]
	v_mfma_f32_16x16x32_bf16 v[136:139], v[104:107], v[194:197], v[136:139]
	v_mfma_f32_16x16x32_bf16 v[132:135], v[154:157], v[194:197], v[132:135]
	v_mfma_f32_16x16x32_bf16 v[128:131], v[104:107], v[202:205], v[128:131]
	v_mfma_f32_16x16x32_bf16 v[124:127], v[154:157], v[202:205], v[124:127]
	v_mfma_f32_16x16x32_bf16 v[120:123], v[104:107], v[210:213], v[120:123]
	v_mfma_f32_16x16x32_bf16 v[116:119], v[154:157], v[210:213], v[116:119]
	v_mfma_f32_16x16x32_bf16 v[112:115], v[104:107], v[218:221], v[112:115]
	v_mfma_f32_16x16x32_bf16 v[108:111], v[154:157], v[218:221], v[108:111]
	v_mfma_f32_16x16x32_bf16 v[64:67], v[158:161], v[190:193], v[64:67]
	v_mfma_f32_16x16x32_bf16 v[60:63], v[166:169], v[190:193], v[60:63]
	v_mfma_f32_16x16x32_bf16 v[56:59], v[158:161], v[198:201], v[56:59]
	v_mfma_f32_16x16x32_bf16 v[52:55], v[166:169], v[198:201], v[52:55]
	v_mfma_f32_16x16x32_bf16 v[48:51], v[158:161], v[206:209], v[48:51]
	v_mfma_f32_16x16x32_bf16 v[44:47], v[166:169], v[206:209], v[44:47]
	v_mfma_f32_16x16x32_bf16 v[40:43], v[158:161], v[214:217], v[40:43]
	v_mfma_f32_16x16x32_bf16 v[36:39], v[166:169], v[214:217], v[36:39]
	v_mfma_f32_16x16x32_bf16 v[64:67], v[162:165], v[194:197], v[64:67]
	v_mfma_f32_16x16x32_bf16 v[60:63], v[186:189], v[194:197], v[60:63]
	v_mfma_f32_16x16x32_bf16 v[56:59], v[162:165], v[202:205], v[56:59]
	v_mfma_f32_16x16x32_bf16 v[52:55], v[186:189], v[202:205], v[52:55]
	v_mfma_f32_16x16x32_bf16 v[48:51], v[162:165], v[210:213], v[48:51]
	v_mfma_f32_16x16x32_bf16 v[44:47], v[186:189], v[210:213], v[44:47]
	v_mfma_f32_16x16x32_bf16 v[40:43], v[162:165], v[218:221], v[40:43]
	v_mfma_f32_16x16x32_bf16 v[36:39], v[186:189], v[218:221], v[36:39]
	s_barrier
; #define PG8_STAGE(bufoff, gbase, voff) do { _Pragma("unroll") for (int _i = 0; _i < 2; ++_i) \
;         __builtin_amdgcn_global_load_lds((const unsigned*)((const char*)(gbase) + (voff)[_i]), (PG8_LAS unsigned*)(lds + (bufoff) + ldsw + _i * 8192), 16, 0, 0); } while (0)
; #define PG8_LDA(dst, b, h) do { _Pragma("unroll") for (int m = 0; m < 4; ++m) _Pragma("unroll") for (int k = 0; k < 2; ++k) dst[m][k] = *(const PG8_LAS bf16x8*)(lds + PG8_SA(b, h) + aoff + m * 2048 + k * 1024); } while (0)
; #define PG8_MMA(ai, bj, At, Bt) do { __builtin_amdgcn_s_setprio(1); _Pragma("unroll") for (int m = 0; m < 4; ++m) _Pragma("unroll") for (int n = 0; n < 2; ++n) _Pragma("unroll") for (int k = 0; k < 2; ++k) \
;         acc[ai][bj][m][n] = __builtin_amdgcn_mfma_f32_16x16x32_bf16(Bt[n][k], At[m][k], acc[ai][bj][m][n], 0, 0, 0); __builtin_amdgcn_s_setprio(0); } while (0)
; #define PG8_WAIT_V(n) asm volatile("s_waitcnt vmcnt(" #n ")" ::: "memory")
; #define PG8_WAIT_L(n) asm volatile("s_waitcnt lgkmcnt(" #n ")" ::: "memory")
; #define PG8_BAR __builtin_amdgcn_s_barrier()
; #define PG8_SCHED __builtin_amdgcn_sched_barrier(0)
; #define GAS __attribute__((address_space(1)))
; __device__ __forceinline__ v4u pack8(const float (&f)[8]) { v4u o; o.x = cvt_pk_bf16(f[0], f[1]); o.y = cvt_pk_bf16(f[2], f[3]); o.z = cvt_pk_bf16(f[4], f[5]); o.w = cvt_pk_bf16(f[6], f[7]); return o; }
; template <class Epi, class Sched, bool ALIGN_EPI = false, bool SP2 = false>
; __device__ __forceinline__ void gemm_phase(PG8_LAS unsigned char* lds, const Gemm g, const Sched& S, const Epi& E) {
;     ...
;             PG8_LDA(At, 1, 1); PG8_STAGE(PG8_SB(1, 0), b3, voffB); PG8_STAGE(PG8_SB(1, 1), b3 + hstep, voffB); PG8_STAGE(PG8_SA(1, 0), a3, voffA);
;             PG8_WAIT_V(8); PG8_WAIT_L(0); PG8_BAR; PG8_MMA(1, 0, At, B0); PG8_MMA(1, 1, At, B1); PG8_BAR; PG8_SCHED;
; __device__ __forceinline__ void phase_gnorm(const Params& P, int seg) {
;     ...
; #pragma unroll
;             for (int e = 0; e < 8; ++e) f[e] *= rs;
;             *(GAS v4u*)(p + g * 512) = pack8(f); } }
	s_add_i32 s16, s59, s28
	v_lshl_add_u64 v[222:223], v[222:223], 0, s[10:11]
	s_mov_b32 m0, s16
	ds_read_b128 v[190:193], v184 offset:49152
	ds_read_b128 v[194:197], v184 offset:50176
	ds_read_b128 v[198:201], v184 offset:51200
	ds_read_b128 v[202:205], v184 offset:52224
	ds_read_b128 v[206:209], v184 offset:53248
	ds_read_b128 v[210:213], v184 offset:54272
	ds_read_b128 v[214:217], v184 offset:55296
	ds_read_b128 v[218:221], v184 offset:56320
	v_lshlrev_b32_e32 v232, 16, v244
	v_and_b32_e32 v233, 0xffff0000, v244
	v_mul_f32_e32 v232, v235, v232
	v_mul_f32_e32 v233, v235, v233
	v_cvt_pk_bf16_f32 v244, v232, v233
	v_lshlrev_b32_e32 v232, 16, v245
	v_and_b32_e32 v233, 0xffff0000, v245
	v_mul_f32_e32 v232, v235, v232
	v_mul_f32_e32 v233, v235, v233
	v_cvt_pk_bf16_f32 v245, v232, v233
	v_lshlrev_b32_e32 v232, 16, v246
	v_and_b32_e32 v233, 0xffff0000, v246
	v_mul_f32_e32 v232, v235, v232
	v_mul_f32_e32 v233, v235, v233
	v_cvt_pk_bf16_f32 v246, v232, v233
	v_lshlrev_b32_e32 v232, 16, v247
	v_and_b32_e32 v233, 0xffff0000, v247
	v_mul_f32_e32 v232, v235, v232
	v_mul_f32_e32 v233, v235, v233
	v_cvt_pk_bf16_f32 v247, v232, v233
	global_load_lds_dwordx4 v[222:223], off
	s_add_i32 m0, s16, 0x2000
	s_add_u32 s14, s14, 0x80080
	v_lshl_add_u64 v[222:223], v[224:225], 0, s[10:11]
	s_addc_u32 s15, s15, 0
	s_add_i32 s16, s60, s28
	global_load_lds_dwordx4 v[222:223], off
	v_lshl_add_u64 v[222:223], s[14:15], 0, v[174:175]
	s_mov_b32 m0, s16
	s_nop 0
	global_load_lds_dwordx4 v[222:223], off
	v_lshl_add_u64 v[222:223], s[14:15], 0, v[144:145]
	s_add_i32 m0, s16, 0x2000
	s_nop 0
	global_load_lds_dwordx4 v[222:223], off
	v_lshl_add_u64 v[222:223], v[226:227], 0, s[10:11]
	s_mov_b32 m0, s35
	s_nop 0
	global_load_lds_dwordx4 v[222:223], off
	v_lshl_add_u64 v[222:223], v[228:229], 0, s[10:11]
	s_mov_b32 m0, s38
	s_nop 0
	global_load_lds_dwordx4 v[222:223], off
	global_store_dwordx4 v236, v[244:247], s[98:99]
	s_and_b32 s63, s84, 7
	s_lshl_b32 s65, s82, 16
	s_sub_u32 s65, s65, 0x1c00
	s_cmp_eq_u32 s63, 7
	s_cselect_b32 s64, s65, 0x400
	s_add_u32 s98, s98, s64
	s_addc_u32 s99, s99, 0
	s_add_i32 s84, s84, 1
	s_add_i32 s32, s32, 0x400
	s_cmp_ge_u32 s32, 0xc00
	s_cselect_b32 s32, 0, s32
	v_readfirstlane_b32 s63, v237
	s_add_i32 s64, s32, 0x800
	s_cmp_ge_u32 s64, 0xc00
	s_cselect_b32 s65, 0xc00, 0
	s_sub_i32 s64, s64, s65
	s_add_i32 m0, s63, s64
	s_nop 0
	global_load_lds_dwordx4 v236, s[100:101]
	s_add_i32 s66, s84, 2
	s_and_b32 s66, s66, 7
	s_lshl_b32 s65, s82, 16
	s_sub_u32 s65, s65, 0x1c00
	s_cmp_eq_u32 s66, 7
	s_cselect_b32 s64, s65, 0x400
	s_add_u32 s100, s100, s64
	s_addc_u32 s101, s101, 0
	s_waitcnt vmcnt(10)
	s_waitcnt lgkmcnt(0)
	s_barrier
	s_waitcnt lgkmcnt(0)
	v_mfma_f32_16x16x32_bf16 v[96:99], v[100:103], v[190:193], v[96:99]
	v_mfma_f32_16x16x32_bf16 v[92:95], v[140:143], v[190:193], v[92:95]
	v_mfma_f32_16x16x32_bf16 v[88:91], v[100:103], v[198:201], v[88:91]
	v_mfma_f32_16x16x32_bf16 v[84:87], v[140:143], v[198:201], v[84:87]
	v_mfma_f32_16x16x32_bf16 v[80:83], v[100:103], v[206:209], v[80:83]
	v_mfma_f32_16x16x32_bf16 v[76:79], v[140:143], v[206:209], v[76:79]
	v_mfma_f32_16x16x32_bf16 v[72:75], v[100:103], v[214:217], v[72:75]
	v_mfma_f32_16x16x32_bf16 v[68:71], v[140:143], v[214:217], v[68:71]
	v_mfma_f32_16x16x32_bf16 v[96:99], v[104:107], v[194:197], v[96:99]
	v_mfma_f32_16x16x32_bf16 v[92:95], v[154:157], v[194:197], v[92:95]
	v_mfma_f32_16x16x32_bf16 v[88:91], v[104:107], v[202:205], v[88:91]
	v_mfma_f32_16x16x32_bf16 v[84:87], v[154:157], v[202:205], v[84:87]
	v_mfma_f32_16x16x32_bf16 v[80:83], v[104:107], v[210:213], v[80:83]
	v_mfma_f32_16x16x32_bf16 v[76:79], v[154:157], v[210:213], v[76:79]
	v_mfma_f32_16x16x32_bf16 v[72:75], v[104:107], v[218:221], v[72:75]
	v_mfma_f32_16x16x32_bf16 v[68:71], v[154:157], v[218:221], v[68:71]
	v_mfma_f32_16x16x32_bf16 v[32:35], v[158:161], v[190:193], v[32:35]
	v_mfma_f32_16x16x32_bf16 v[28:31], v[166:169], v[190:193], v[28:31]
	v_mfma_f32_16x16x32_bf16 v[24:27], v[158:161], v[198:201], v[24:27]
	v_mfma_f32_16x16x32_bf16 v[20:23], v[166:169], v[198:201], v[20:23]
	v_mfma_f32_16x16x32_bf16 v[16:19], v[158:161], v[206:209], v[16:19]
	v_mfma_f32_16x16x32_bf16 v[12:15], v[166:169], v[206:209], v[12:15]
	v_mfma_f32_16x16x32_bf16 v[8:11], v[158:161], v[214:217], v[8:11]
	v_mfma_f32_16x16x32_bf16 v[4:7], v[166:169], v[214:217], v[4:7]
	v_mfma_f32_16x16x32_bf16 v[32:35], v[162:165], v[194:197], v[32:35]
	v_mfma_f32_16x16x32_bf16 v[28:31], v[186:189], v[194:197], v[28:31]
	v_mfma_f32_16x16x32_bf16 v[24:27], v[162:165], v[202:205], v[24:27]
	v_mfma_f32_16x16x32_bf16 v[20:23], v[186:189], v[202:205], v[20:23]
	v_mfma_f32_16x16x32_bf16 v[16:19], v[162:165], v[210:213], v[16:19]
	v_mfma_f32_16x16x32_bf16 v[12:15], v[186:189], v[210:213], v[12:15]
	v_mfma_f32_16x16x32_bf16 v[8:11], v[162:165], v[218:221], v[8:11]
	v_mfma_f32_16x16x32_bf16 v[4:7], v[186:189], v[218:221], v[4:7]
	s_barrier
	s_add_i32 s58, s58, 2
	s_add_u32 s51, s51, 0x100
	s_addc_u32 s57, s57, 0
	s_add_u32 s0, s0, 0x100
	s_addc_u32 s1, s1, 0
	s_cmp_gt_u32 s58, 29
	s_cbranch_scc0 .LBB0_407
	s_and_b64 vcc, exec, s[46:47]
	s_cbranch_vccz .LBB0_410
	s_barrier

; #define LAS __attribute__((address_space(3)))
; __global__ void __launch_bounds__(NTHREADS, 2) hybrid_fwd(Params P) {
;     extern __shared__ __attribute__((aligned(16))) unsigned char smem[];
;     cg::grid_group grid = cg::this_grid();
;     gws_t ws = (gws_t)P.ws;
;     volatile LAS unsigned* xst = (volatile LAS unsigned*)(smem + LDS_STAGE);
	.amdhsa_kernel _Z10hybrid_fwd6Params
		.amdhsa_group_segment_fixed_size 24576
		.amdhsa_private_segment_fixed_size 0
		.amdhsa_kernarg_size 440
		.amdhsa_user_sgpr_count 2
		.amdhsa_user_sgpr_dispatch_ptr 0
		.amdhsa_user_sgpr_queue_ptr 0
		.amdhsa_user_sgpr_kernarg_segment_ptr 1
		.amdhsa_user_sgpr_dispatch_id 0
		.amdhsa_user_sgpr_kernarg_preload_length 0
		.amdhsa_user_sgpr_kernarg_preload_offset 0
		.amdhsa_user_sgpr_private_segment_size 0
		.amdhsa_uses_dynamic_stack 0
		.amdhsa_enable_private_segment 0
		.amdhsa_system_sgpr_workgroup_id_x 1
		.amdhsa_system_sgpr_workgroup_id_y 0
		.amdhsa_system_sgpr_workgroup_id_z 0
		.amdhsa_system_sgpr_workgroup_info 0
		.amdhsa_system_vgpr_workitem_id 2
		.amdhsa_next_free_vgpr 256
		.amdhsa_next_free_sgpr 102
		.amdhsa_accum_offset 256
		.amdhsa_reserve_vcc 1
		.amdhsa_float_round_mode_32 0
		.amdhsa_float_round_mode_16_64 0
		.amdhsa_float_denorm_mode_32 3
		.amdhsa_float_denorm_mode_16_64 3
		.amdhsa_dx10_clamp 1
		.amdhsa_ieee_mode 1
		.amdhsa_fp16_overflow 0
		.amdhsa_tg_split 0
		.amdhsa_exception_fp_ieee_invalid_op 0
		.amdhsa_exception_fp_denorm_src 0
		.amdhsa_exception_fp_ieee_div_zero 0
		.amdhsa_exception_fp_ieee_overflow 0
		.amdhsa_exception_fp_ieee_underflow 0
		.amdhsa_exception_fp_ieee_inexact 0
		.amdhsa_exception_int_div_zero 0
	.end_amdhsa_kernel

; #define LAS __attribute__((address_space(3)))
; __global__ void __launch_bounds__(NTHREADS, 2) hybrid_fwd(Params P) {
;     extern __shared__ __attribute__((aligned(16))) unsigned char smem[];
;     cg::grid_group grid = cg::this_grid();
;     gws_t ws = (gws_t)P.ws;
;     volatile LAS unsigned* xst = (volatile LAS unsigned*)(smem + LDS_STAGE);
amdhsa.kernels:
  - .agpr_count:     0
    .args:
      - .offset:         0
        .size:           184
        .value_kind:     by_value
      - .offset:         184
        .size:           4
        .value_kind:     hidden_block_count_x
      - .offset:         188
        .size:           4
        .value_kind:     hidden_block_count_y
      - .offset:         192
        .size:           4
        .value_kind:     hidden_block_count_z
      - .offset:         196
        .size:           2
        .value_kind:     hidden_group_size_x
      - .offset:         198
        .size:           2
        .value_kind:     hidden_group_size_y
      - .offset:         200
        .size:           2
        .value_kind:     hidden_group_size_z
      - .offset:         202
        .size:           2
        .value_kind:     hidden_remainder_x
      - .offset:         204
        .size:           2
        .value_kind:     hidden_remainder_y
      - .offset:         206
        .size:           2
        .value_kind:     hidden_remainder_z
      - .offset:         224
        .size:           8
        .value_kind:     hidden_global_offset_x
      - .offset:         232
        .size:           8
        .value_kind:     hidden_global_offset_y
      - .offset:         240
        .size:           8
        .value_kind:     hidden_global_offset_z
      - .offset:         248
        .size:           2
        .value_kind:     hidden_grid_dims
      - .offset:         272
        .size:           8
        .value_kind:     hidden_multigrid_sync_arg
      - .offset:         304
        .size:           4
        .value_kind:     hidden_dynamic_lds_size
    .group_segment_fixed_size: 24576
    .kernarg_segment_align: 8
    .kernarg_segment_size: 440
    .language:       OpenCL C
    .language_version:
      - 2
      - 0
    .max_flat_workgroup_size: 512
    .name:           _Z10hybrid_fwd6Params
    .private_segment_fixed_size: 0
    .sgpr_count:     108
    .sgpr_spill_count: 217
    .symbol:         _Z10hybrid_fwd6Params.kd
    .uniform_work_group_size: 1
    .uses_dynamic_stack: false
    .vgpr_count:     256
    .vgpr_spill_count: 0
    .wavefront_size: 64
